# kv_local GLA path: batched tile loads + V prefetch + batched write-back (removes 22 serialized round trips)
# speedup vs baseline: 1.0218x; 1.0218x over previous
.LBB0_383:
	s_and_b32 s75, s2, 7
	s_ashr_i32 s78, s2, 3
	s_lshl_b32 s60, s75, 11
	s_lshl_b32 s58, s78, 6
	s_add_i32 s59, s58, s60
	s_mul_hi_i32 s65, s59, 0x1e00
	s_mul_i32 s66, s59, 0x1e00
	s_and_b32 s61, s64, 3
	s_lshl_b32 s4, s61, 6
	v_and_b32_e32 v43, 7, v64
	v_ashrrev_i32_e32 v42, 3, v64
	s_cmp_gt_u32 s64, 3
	s_mov_b64 s[34:35], -1
	v_lshlrev_b32_e32 v32, 4, v43
	v_cmp_gt_i32_e64 s[40:41], 64, v42
	s_cbranch_scc0 .LBB0_475
	s_waitcnt lgkmcnt(0)
	s_add_u32 s5, s20, s66
	s_addc_u32 s7, s21, s65
	s_lshl_b32 s6, s4, 1
	s_add_u32 s6, s5, s6
	s_addc_u32 s7, s7, 0
	v_mov_b32_e32 v33, v193
	v_lshl_add_u64 v[22:23], s[6:7], 0, v[32:33]
	v_lshl_add_u32 v6, v43, 4, s33
	v_mul_lo_u32 v1, v42, s85
	v_add_u32_e32 v45, v6, v1
	v_add_u32_e32 v1, 64, v64
	v_ashrrev_i32_e32 v33, 3, v1
	v_cmp_gt_i32_e64 s[42:43], 64, v33
	v_mul_lo_u32 v4, v33, s85
	v_add_u32_e32 v47, v6, v4
	v_add_u32_e32 v1, 0x80, v64
	v_ashrrev_i32_e32 v44, 3, v1
	v_cmp_gt_i32_e64 s[44:45], 64, v44
	v_mul_lo_u32 v4, v44, s85
	v_add_u32_e32 v49, v6, v4
	v_add_u32_e32 v1, 0xc0, v64
	v_ashrrev_i32_e32 v46, 3, v1
	v_cmp_gt_i32_e64 s[46:47], 64, v46
	v_mul_lo_u32 v4, v46, s85
	v_add_u32_e32 v51, v6, v4
	v_add_u32_e32 v1, 0x100, v64
	v_ashrrev_i32_e32 v48, 3, v1
	v_cmp_gt_i32_e64 s[48:49], 64, v48
	v_mul_lo_u32 v4, v48, s85
	v_add_u32_e32 v53, v6, v4
	v_add_u32_e32 v1, 0x140, v64
	v_ashrrev_i32_e32 v50, 3, v1
	v_cmp_gt_i32_e64 s[50:51], 64, v50
	v_mul_lo_u32 v4, v50, s85
	v_add_u32_e32 v55, v6, v4
	v_add_u32_e32 v1, 0x180, v64
	v_ashrrev_i32_e32 v52, 3, v1
	v_cmp_gt_i32_e64 s[52:53], 64, v52
	v_mul_lo_u32 v4, v52, s85
	v_add_u32_e32 v56, v6, v4
	v_add_u32_e32 v1, 0x1c0, v64
	v_ashrrev_i32_e32 v54, 3, v1
	v_cmp_gt_i32_e64 s[54:55], 64, v54
	v_mul_lo_u32 v4, v54, s85
	v_add_u32_e32 v57, v6, v4
	s_add_u32 s34, s20, 0xf600000
	v_add_u32_e32 v16, s59, v64
	s_addc_u32 s35, s21, 0
	v_ashrrev_i32_e32 v17, 31, v16
	v_lshlrev_b64 v[20:21], 6, v[16:17]
	v_lshl_add_u64 v[20:21], s[34:35], 0, v[20:21]
	global_load_dwordx4 v[4:7], v[20:21], off
	global_load_dwordx4 v[0:3], v[20:21], off offset:16
	global_load_dwordx4 v[12:15], v[20:21], off offset:32
	global_load_dwordx4 v[8:11], v[20:21], off offset:48
	v_add_u32_e32 v16, s4, v64
	s_add_u32 s30, s30, s62
	v_ashrrev_i32_e32 v17, 31, v16
	s_addc_u32 s31, s31, s63
	v_lshlrev_b64 v[18:19], 2, v[16:17]
	v_lshl_add_u64 v[20:21], s[30:31], 0, v[18:19]
	global_load_dword v24, v[20:21], off
	global_load_dword v25, v[20:21], off offset:1024
	global_load_dword v26, v[20:21], off offset:2048
	global_load_dword v27, v[20:21], off offset:3072
	v_add_u32_e32 v20, 0x400, v16
	v_ashrrev_i32_e32 v21, 31, v20
	v_lshl_add_u64 v[20:21], v[20:21], 2, s[30:31]
	global_load_dword v28, v[20:21], off
	v_add_u32_e32 v20, 0x500, v16
	v_ashrrev_i32_e32 v21, 31, v20
	v_lshl_add_u64 v[20:21], v[20:21], 2, s[30:31]
	global_load_dword v29, v[20:21], off
	v_add_u32_e32 v20, 0x600, v16
	v_ashrrev_i32_e32 v21, 31, v20
	v_lshl_add_u64 v[20:21], v[20:21], 2, s[30:31]
	global_load_dword v30, v[20:21], off
	v_add_u32_e32 v20, 0x700, v16
	v_ashrrev_i32_e32 v21, 31, v20
	v_lshl_add_u64 v[20:21], v[20:21], 2, s[30:31]
	global_load_dword v31, v[20:21], off
	v_add_u32_e32 v20, 0x800, v16
	v_ashrrev_i32_e32 v21, 31, v20
	v_lshl_add_u64 v[20:21], v[20:21], 2, s[30:31]
	global_load_dword v34, v[20:21], off
	v_add_u32_e32 v20, 0x900, v16
	v_ashrrev_i32_e32 v21, 31, v20
	v_lshl_add_u64 v[20:21], v[20:21], 2, s[30:31]
	global_load_dword v35, v[20:21], off
	v_add_u32_e32 v20, 0xa00, v16
	v_ashrrev_i32_e32 v21, 31, v20
	v_lshl_add_u64 v[20:21], v[20:21], 2, s[30:31]
	global_load_dword v36, v[20:21], off
	v_add_u32_e32 v20, 0xb00, v16
	v_ashrrev_i32_e32 v21, 31, v20
	v_lshl_add_u64 v[20:21], v[20:21], 2, s[30:31]
	global_load_dword v37, v[20:21], off
	v_add_u32_e32 v20, 0xc00, v16
	v_ashrrev_i32_e32 v21, 31, v20
	v_lshl_add_u64 v[20:21], v[20:21], 2, s[30:31]
	global_load_dword v38, v[20:21], off
	v_add_u32_e32 v20, 0xd00, v16
	v_ashrrev_i32_e32 v21, 31, v20
	v_lshl_add_u64 v[20:21], v[20:21], 2, s[30:31]
	s_lshl_b64 s[6:7], s[36:37], 2
	global_load_dword v39, v[20:21], off
	v_add_u32_e32 v20, 0xe00, v16
	v_add_u32_e32 v16, 0xf00, v16
	s_add_u32 s22, s22, s6
	v_ashrrev_i32_e32 v21, 31, v20
	v_ashrrev_i32_e32 v17, 31, v16
	s_addc_u32 s23, s23, s7
	v_lshl_add_u64 v[20:21], v[20:21], 2, s[30:31]
	v_lshl_add_u64 v[16:17], v[16:17], 2, s[30:31]
	global_load_dword v40, v[20:21], off
	global_load_dword v41, v[16:17], off
	v_lshl_add_u64 v[16:17], s[22:23], 0, v[18:19]
	global_load_dword v192, v[16:17], off
	v_mad_i64_i32 v[16:17], s[6:7], v42, s84, v[22:23]
	global_load_dwordx4 v[96:99], v[16:17], off offset:2560
	global_load_dwordx4 v[160:163], v[16:17], off offset:2048
	global_load_dwordx4 v[128:131], v[16:17], off offset:3072
	v_mad_i64_i32 v[16:17], s[6:7], v33, s84, v[22:23]
	global_load_dwordx4 v[100:103], v[16:17], off offset:2560
	global_load_dwordx4 v[164:167], v[16:17], off offset:2048
	global_load_dwordx4 v[132:135], v[16:17], off offset:3072
	v_mad_i64_i32 v[16:17], s[6:7], v44, s84, v[22:23]
	global_load_dwordx4 v[104:107], v[16:17], off offset:2560
	global_load_dwordx4 v[168:171], v[16:17], off offset:2048
	global_load_dwordx4 v[136:139], v[16:17], off offset:3072
	v_mad_i64_i32 v[16:17], s[6:7], v46, s84, v[22:23]
	global_load_dwordx4 v[108:111], v[16:17], off offset:2560
	global_load_dwordx4 v[172:175], v[16:17], off offset:2048
	global_load_dwordx4 v[140:143], v[16:17], off offset:3072
	v_mad_i64_i32 v[16:17], s[6:7], v48, s84, v[22:23]
	global_load_dwordx4 v[112:115], v[16:17], off offset:2560
	global_load_dwordx4 v[176:179], v[16:17], off offset:2048
	global_load_dwordx4 v[144:147], v[16:17], off offset:3072
	v_mad_i64_i32 v[16:17], s[6:7], v50, s84, v[22:23]
	global_load_dwordx4 v[116:119], v[16:17], off offset:2560
	global_load_dwordx4 v[180:183], v[16:17], off offset:2048
	global_load_dwordx4 v[148:151], v[16:17], off offset:3072
	v_mad_i64_i32 v[16:17], s[6:7], v52, s84, v[22:23]
	global_load_dwordx4 v[120:123], v[16:17], off offset:2560
	global_load_dwordx4 v[184:187], v[16:17], off offset:2048
	global_load_dwordx4 v[152:155], v[16:17], off offset:3072
	v_mad_i64_i32 v[16:17], s[6:7], v54, s84, v[22:23]
	global_load_dwordx4 v[124:127], v[16:17], off offset:2560
	global_load_dwordx4 v[188:191], v[16:17], off offset:2048
	global_load_dwordx4 v[156:159], v[16:17], off offset:3072
	s_waitcnt vmcnt(23)
	ds_write_b128 v45, v[96:99]
	s_waitcnt vmcnt(22)
	ds_write_b128 v45, v[160:163] offset:9216
	s_waitcnt vmcnt(20)
	ds_write_b128 v47, v[100:103]
	s_waitcnt vmcnt(19)
	ds_write_b128 v47, v[164:167] offset:9216
	s_waitcnt vmcnt(17)
	ds_write_b128 v49, v[104:107]
	s_waitcnt vmcnt(16)
	ds_write_b128 v49, v[168:171] offset:9216
	s_waitcnt vmcnt(14)
	ds_write_b128 v51, v[108:111]
	s_waitcnt vmcnt(13)
	ds_write_b128 v51, v[172:175] offset:9216
	s_waitcnt vmcnt(11)
	ds_write_b128 v53, v[112:115]
	s_waitcnt vmcnt(10)
	ds_write_b128 v53, v[176:179] offset:9216
	s_waitcnt vmcnt(8)
	ds_write_b128 v55, v[116:119]
	s_waitcnt vmcnt(7)
	ds_write_b128 v55, v[180:183] offset:9216
	s_waitcnt vmcnt(5)
	ds_write_b128 v56, v[120:123]
	s_waitcnt vmcnt(4)
	ds_write_b128 v56, v[184:187] offset:9216
	s_waitcnt vmcnt(2)
	ds_write_b128 v57, v[124:127]
	s_waitcnt vmcnt(1)
	ds_write_b128 v57, v[188:191] offset:9216
	v_lshl_add_u32 v16, v64, 1, s33
	s_mov_b32 s5, 0
	v_mov_b32_e32 v17, 0
.LBB0_425:
	v_readlane_b32 s6, v4, s5
	v_readlane_b32 s7, v5, s5
	v_readlane_b32 s8, v6, s5
	v_readlane_b32 s9, v7, s5
	v_pk_fma_f32 v[18:19], v[24:25], s[6:7], v[192:193]
	v_readlane_b32 s10, v0, s5
	v_readlane_b32 s11, v1, s5
	v_pk_fma_f32 v[18:19], v[26:27], s[8:9], v[18:19]
	v_readlane_b32 s22, v2, s5
	v_readlane_b32 s23, v3, s5
	v_pk_fma_f32 v[18:19], v[28:29], s[10:11], v[18:19]
	v_readlane_b32 s30, v12, s5
	v_readlane_b32 s31, v13, s5
	v_pk_fma_f32 v[18:19], v[30:31], s[22:23], v[18:19]
	v_readlane_b32 s34, v14, s5
	v_readlane_b32 s35, v15, s5
	v_pk_fma_f32 v[18:19], v[34:35], s[30:31], v[18:19]
	v_readlane_b32 s38, v8, s5
	v_readlane_b32 s39, v9, s5
	v_pk_fma_f32 v[18:19], v[36:37], s[34:35], v[18:19]
	v_readlane_b32 s56, v10, s5
	v_readlane_b32 s57, v11, s5
	v_pk_fma_f32 v[18:19], v[38:39], s[38:39], v[18:19]
	s_add_i32 s12, s5, 1
	v_pk_fma_f32 v[18:19], v[40:41], s[56:57], v[18:19]
	v_readlane_b32 s8, v6, s12
	v_add_f32_e32 v18, v18, v19
	v_min_f32_e32 v19, 0, v18
	v_mul_f32_e64 v18, |v18|, s87
	v_exp_f32_e32 v18, v18
	v_readlane_b32 s9, v7, s12
	v_readlane_b32 s10, v0, s12
	v_readlane_b32 s11, v1, s12
	v_add_f32_e32 v18, 1.0, v18
	v_cmp_gt_f32_e32 vcc, s86, v18
	v_readlane_b32 s22, v2, s12
	v_readlane_b32 s23, v3, s12
	v_cndmask_b32_e64 v20, 0, 32, vcc
	v_ldexp_f32 v18, v18, v20
	v_log_f32_e32 v18, v18
	v_readlane_b32 s30, v12, s12
	v_readlane_b32 s31, v13, s12
	v_readlane_b32 s34, v14, s12
	v_mul_f32_e32 v20, 0x3f317217, v18
	v_fma_f32 v20, v18, s88, -v20
	v_fmac_f32_e32 v20, 0x3377d1cf, v18
	v_fmac_f32_e32 v20, 0x3f317217, v18
	v_cmp_lt_f32_e64 s[56:57], |v18|, s89
	v_readlane_b32 s35, v15, s12
	v_readlane_b32 s38, v8, s12
	v_cndmask_b32_e64 v18, v18, v20, s[56:57]
	v_cndmask_b32_e32 v20, 0, v239, vcc
	v_sub_f32_e32 v18, v18, v20
	v_sub_f32_e32 v18, v19, v18
	v_fmac_f32_e32 v17, 0x3d800000, v18
	ds_read_u16 v19, v16
	v_mul_f32_e32 v18, 0x3fb8aa3b, v17
	v_exp_f32_e32 v18, v18
	v_readlane_b32 s39, v9, s12
	v_readlane_b32 s56, v10, s12
	s_waitcnt lgkmcnt(0)
	v_lshlrev_b32_e32 v19, 16, v19
	v_div_scale_f32 v20, s[6:7], v18, v18, v19
	v_rcp_f32_e32 v21, v20
	v_readlane_b32 s6, v4, s12
	v_readlane_b32 s7, v5, s12
	v_readlane_b32 s57, v11, s12
	v_fma_f32 v58, -v20, v21, 1.0
	v_fmac_f32_e32 v21, v58, v21
	v_div_scale_f32 v58, vcc, v19, v18, v19
	v_mul_f32_e32 v59, v58, v21
	v_fma_f32 v60, -v20, v59, v58
	v_fmac_f32_e32 v59, v60, v21
	v_fma_f32 v20, -v20, v59, v58
	v_div_fmas_f32 v20, v20, v21, v59
	v_div_fixup_f32 v19, v20, v18, v19
	v_cvt_pk_bf16_f32 v19, v19, s0
	ds_write_b16 v16, v19
	ds_read_u16 v19, v16 offset:9216
	s_add_i32 s12, s5, 2
	s_waitcnt lgkmcnt(0)
	v_lshlrev_b32_e32 v19, 16, v19
	v_mul_f32_e32 v19, 0x3e000000, v19
	v_mul_f32_e32 v18, v19, v18
	v_cvt_pk_bf16_f32 v18, v18, s0
	ds_write_b16 v16, v18 offset:9216
	v_pk_fma_f32 v[18:19], v[24:25], s[6:7], v[192:193]
	s_nop 0
	v_pk_fma_f32 v[18:19], v[26:27], s[8:9], v[18:19]
	v_readlane_b32 s8, v6, s12
	v_pk_fma_f32 v[18:19], v[28:29], s[10:11], v[18:19]
	v_readlane_b32 s9, v7, s12
	v_pk_fma_f32 v[18:19], v[30:31], s[22:23], v[18:19]
	v_readlane_b32 s10, v0, s12
	v_pk_fma_f32 v[18:19], v[34:35], s[30:31], v[18:19]
	v_readlane_b32 s11, v1, s12
	v_pk_fma_f32 v[18:19], v[36:37], s[34:35], v[18:19]
	v_readlane_b32 s22, v2, s12
	v_pk_fma_f32 v[18:19], v[38:39], s[38:39], v[18:19]
	v_readlane_b32 s23, v3, s12
	v_pk_fma_f32 v[18:19], v[40:41], s[56:57], v[18:19]
	v_readlane_b32 s30, v12, s12
	v_add_f32_e32 v18, v18, v19
	v_min_f32_e32 v19, 0, v18
	v_mul_f32_e64 v18, |v18|, s87
	v_exp_f32_e32 v18, v18
	v_readlane_b32 s31, v13, s12
	v_readlane_b32 s34, v14, s12
	v_readlane_b32 s35, v15, s12
	v_add_f32_e32 v18, 1.0, v18
	v_cmp_gt_f32_e32 vcc, s86, v18
	v_readlane_b32 s38, v8, s12
	v_readlane_b32 s39, v9, s12
	v_cndmask_b32_e64 v20, 0, 32, vcc
	v_ldexp_f32 v18, v18, v20
	v_log_f32_e32 v18, v18
	s_nop 0
	v_mul_f32_e32 v20, 0x3f317217, v18
	v_fma_f32 v20, v18, s88, -v20
	v_fmac_f32_e32 v20, 0x3377d1cf, v18
	v_fmac_f32_e32 v20, 0x3f317217, v18
	v_cmp_lt_f32_e64 s[56:57], |v18|, s89
	s_nop 1
	v_cndmask_b32_e64 v18, v18, v20, s[56:57]
	v_cndmask_b32_e32 v20, 0, v239, vcc
	v_sub_f32_e32 v18, v18, v20
	v_sub_f32_e32 v18, v19, v18
	v_fmac_f32_e32 v17, 0x3d800000, v18
	ds_read_u16 v19, v16 offset:144
	v_mul_f32_e32 v18, 0x3fb8aa3b, v17
	v_exp_f32_e32 v18, v18
	v_readlane_b32 s56, v10, s12
	v_readlane_b32 s57, v11, s12
	s_waitcnt lgkmcnt(0)
	v_lshlrev_b32_e32 v19, 16, v19
	v_div_scale_f32 v20, s[6:7], v18, v18, v19
	v_rcp_f32_e32 v21, v20
	v_readlane_b32 s6, v4, s12
	v_readlane_b32 s7, v5, s12
	s_add_i32 s12, s5, 3
	v_fma_f32 v58, -v20, v21, 1.0
	v_fmac_f32_e32 v21, v58, v21
	v_div_scale_f32 v58, vcc, v19, v18, v19
	v_mul_f32_e32 v59, v58, v21
	v_fma_f32 v60, -v20, v59, v58
	v_fmac_f32_e32 v59, v60, v21
	v_fma_f32 v20, -v20, v59, v58
	v_div_fmas_f32 v20, v20, v21, v59
	v_div_fixup_f32 v19, v20, v18, v19
	v_cvt_pk_bf16_f32 v19, v19, s0
	ds_write_b16 v16, v19 offset:144
	ds_read_u16 v19, v16 offset:9360
	s_add_i32 s5, s5, 4
	s_cmp_eq_u32 s5, 64
	s_waitcnt lgkmcnt(0)
	v_lshlrev_b32_e32 v19, 16, v19
	v_mul_f32_e32 v19, 0x3e000000, v19
	v_mul_f32_e32 v18, v19, v18
	v_cvt_pk_bf16_f32 v18, v18, s0
	ds_write_b16 v16, v18 offset:9360
	v_pk_fma_f32 v[18:19], v[24:25], s[6:7], v[192:193]
	s_nop 0
	v_pk_fma_f32 v[18:19], v[26:27], s[8:9], v[18:19]
	v_readlane_b32 s8, v6, s12
	v_pk_fma_f32 v[18:19], v[28:29], s[10:11], v[18:19]
	v_readlane_b32 s9, v7, s12
	v_pk_fma_f32 v[18:19], v[30:31], s[22:23], v[18:19]
	v_readlane_b32 s10, v0, s12
	v_pk_fma_f32 v[18:19], v[34:35], s[30:31], v[18:19]
	v_readlane_b32 s11, v1, s12
	v_pk_fma_f32 v[18:19], v[36:37], s[34:35], v[18:19]
	v_readlane_b32 s22, v2, s12
	v_pk_fma_f32 v[18:19], v[38:39], s[38:39], v[18:19]
	v_readlane_b32 s23, v3, s12
	v_pk_fma_f32 v[18:19], v[40:41], s[56:57], v[18:19]
	v_readlane_b32 s30, v12, s12
	v_add_f32_e32 v18, v18, v19
	v_min_f32_e32 v19, 0, v18
	v_mul_f32_e64 v18, |v18|, s87
	v_exp_f32_e32 v18, v18
	v_readlane_b32 s31, v13, s12
	v_readlane_b32 s34, v14, s12
	v_readlane_b32 s35, v15, s12
	v_add_f32_e32 v18, 1.0, v18
	v_cmp_gt_f32_e32 vcc, s86, v18
	v_readlane_b32 s38, v8, s12
	v_readlane_b32 s39, v9, s12
	v_cndmask_b32_e64 v20, 0, 32, vcc
	v_ldexp_f32 v18, v18, v20
	v_log_f32_e32 v18, v18
	s_nop 0
	v_mul_f32_e32 v20, 0x3f317217, v18
	v_fma_f32 v20, v18, s88, -v20
	v_fmac_f32_e32 v20, 0x3377d1cf, v18
	v_fmac_f32_e32 v20, 0x3f317217, v18
	v_cmp_lt_f32_e64 s[56:57], |v18|, s89
	s_nop 1
	v_cndmask_b32_e64 v18, v18, v20, s[56:57]
	v_cndmask_b32_e32 v20, 0, v239, vcc
	v_sub_f32_e32 v18, v18, v20
	v_sub_f32_e32 v18, v19, v18
	v_fmac_f32_e32 v17, 0x3d800000, v18
	ds_read_u16 v19, v16 offset:288
	v_mul_f32_e32 v18, 0x3fb8aa3b, v17
	v_exp_f32_e32 v18, v18
	v_readlane_b32 s56, v10, s12
	v_readlane_b32 s57, v11, s12
	s_waitcnt lgkmcnt(0)
	v_lshlrev_b32_e32 v19, 16, v19
	v_div_scale_f32 v20, s[6:7], v18, v18, v19
	v_rcp_f32_e32 v21, v20
	v_readlane_b32 s6, v4, s12
	v_readlane_b32 s7, v5, s12
	v_fma_f32 v58, -v20, v21, 1.0
	v_fmac_f32_e32 v21, v58, v21
	v_div_scale_f32 v58, vcc, v19, v18, v19
	v_mul_f32_e32 v59, v58, v21
	v_fma_f32 v60, -v20, v59, v58
	v_fmac_f32_e32 v59, v60, v21
	v_fma_f32 v20, -v20, v59, v58
	v_div_fmas_f32 v20, v20, v21, v59
	v_div_fixup_f32 v19, v20, v18, v19
	v_cvt_pk_bf16_f32 v19, v19, s0
	ds_write_b16 v16, v19 offset:288
	ds_read_u16 v19, v16 offset:9504
	s_waitcnt lgkmcnt(0)
	v_lshlrev_b32_e32 v19, 16, v19
	v_mul_f32_e32 v19, 0x3e000000, v19
	v_mul_f32_e32 v18, v19, v18
	v_cvt_pk_bf16_f32 v18, v18, s0
	ds_write_b16 v16, v18 offset:9504
	v_pk_fma_f32 v[18:19], v[24:25], s[6:7], v[192:193]
	s_nop 0
	v_pk_fma_f32 v[18:19], v[26:27], s[8:9], v[18:19]
	s_nop 0
	v_pk_fma_f32 v[18:19], v[28:29], s[10:11], v[18:19]
	s_nop 0
	v_pk_fma_f32 v[18:19], v[30:31], s[22:23], v[18:19]
	s_nop 0
	v_pk_fma_f32 v[18:19], v[34:35], s[30:31], v[18:19]
	s_nop 0
	v_pk_fma_f32 v[18:19], v[36:37], s[34:35], v[18:19]
	s_nop 0
	v_pk_fma_f32 v[18:19], v[38:39], s[38:39], v[18:19]
	s_nop 0
	v_pk_fma_f32 v[18:19], v[40:41], s[56:57], v[18:19]
	s_nop 0
	v_add_f32_e32 v18, v18, v19
	v_min_f32_e32 v19, 0, v18
	v_mul_f32_e64 v18, |v18|, s87
	v_exp_f32_e32 v18, v18
	s_nop 0
	v_add_f32_e32 v18, 1.0, v18
	v_cmp_gt_f32_e32 vcc, s86, v18
	s_nop 1
	v_cndmask_b32_e64 v20, 0, 32, vcc
	v_ldexp_f32 v18, v18, v20
	v_log_f32_e32 v18, v18
	s_nop 0
	v_mul_f32_e32 v20, 0x3f317217, v18
	v_fma_f32 v20, v18, s88, -v20
	v_fmac_f32_e32 v20, 0x3377d1cf, v18
	v_fmac_f32_e32 v20, 0x3f317217, v18
	v_cmp_lt_f32_e64 s[56:57], |v18|, s89
	s_nop 1
	v_cndmask_b32_e64 v18, v18, v20, s[56:57]
	v_cndmask_b32_e32 v20, 0, v239, vcc
	v_sub_f32_e32 v18, v18, v20
	v_sub_f32_e32 v18, v19, v18
	v_fmac_f32_e32 v17, 0x3d800000, v18
	v_mul_f32_e32 v18, 0x3fb8aa3b, v17
	v_exp_f32_e32 v68, v18
	ds_read_u16 v18, v16 offset:432
	s_waitcnt lgkmcnt(0)
	v_lshlrev_b32_e32 v18, 16, v18
	v_div_scale_f32 v19, s[6:7], v68, v68, v18
	v_rcp_f32_e32 v20, v19
	s_nop 0
	v_fma_f32 v21, -v19, v20, 1.0
	v_fmac_f32_e32 v20, v21, v20
	v_div_scale_f32 v21, vcc, v18, v68, v18
	v_mul_f32_e32 v58, v21, v20
	v_fma_f32 v59, -v19, v58, v21
	v_fmac_f32_e32 v58, v59, v20
	v_fma_f32 v19, -v19, v58, v21
	v_div_fmas_f32 v19, v19, v20, v58
	v_div_fixup_f32 v18, v19, v68, v18
	v_cvt_pk_bf16_f32 v18, v18, s0
	ds_write_b16 v16, v18 offset:432
	ds_read_u16 v18, v16 offset:9648
	s_waitcnt lgkmcnt(0)
	v_lshlrev_b32_e32 v18, 16, v18
	v_mul_f32_e32 v18, 0x3e000000, v18
	v_mul_f32_e32 v18, v18, v68
	v_cvt_pk_bf16_f32 v18, v18, s0
	ds_write_b16 v16, v18 offset:9648
	v_add_u32_e32 v16, 0x240, v16
	s_cbranch_scc0 .LBB0_425
	s_waitcnt lgkmcnt(0)
	v_mad_i64_i32 v[0:1], s[6:7], v42, s84, v[22:23]
	v_mad_i64_i32 v[2:3], s[6:7], v33, s84, v[22:23]
	v_mad_i64_i32 v[4:5], s[6:7], v44, s84, v[22:23]
	v_mad_i64_i32 v[6:7], s[6:7], v46, s84, v[22:23]
	v_mad_i64_i32 v[8:9], s[6:7], v48, s84, v[22:23]
	v_mad_i64_i32 v[10:11], s[6:7], v50, s84, v[22:23]
	v_mad_i64_i32 v[12:13], s[6:7], v52, s84, v[22:23]
	v_mad_i64_i32 v[14:15], s[6:7], v54, s84, v[22:23]
	ds_read_b128 v[160:163], v45 offset:9216
	ds_read_b128 v[164:167], v47 offset:9216
	ds_read_b128 v[168:171], v49 offset:9216
	ds_read_b128 v[172:175], v51 offset:9216
	ds_read_b128 v[176:179], v53 offset:9216
	ds_read_b128 v[180:183], v55 offset:9216
	ds_read_b128 v[184:187], v56 offset:9216
	ds_read_b128 v[188:191], v57 offset:9216
	s_waitcnt lgkmcnt(7)
	global_store_dwordx4 v[0:1], v[160:163], off offset:2048
	ds_read_b128 v[96:99], v45
	s_waitcnt lgkmcnt(7)
	global_store_dwordx4 v[2:3], v[164:167], off offset:2048
	ds_read_b128 v[100:103], v47
	s_waitcnt lgkmcnt(7)
	global_store_dwordx4 v[4:5], v[168:171], off offset:2048
	ds_read_b128 v[104:107], v49
	s_waitcnt lgkmcnt(7)
	global_store_dwordx4 v[6:7], v[172:175], off offset:2048
	ds_read_b128 v[108:111], v51
	s_waitcnt lgkmcnt(7)
	global_store_dwordx4 v[8:9], v[176:179], off offset:2048
	ds_read_b128 v[112:115], v53
	s_waitcnt lgkmcnt(7)
	global_store_dwordx4 v[10:11], v[180:183], off offset:2048
	ds_read_b128 v[116:119], v55
	s_waitcnt lgkmcnt(7)
	global_store_dwordx4 v[12:13], v[184:187], off offset:2048
	ds_read_b128 v[120:123], v56
	s_waitcnt lgkmcnt(7)
	global_store_dwordx4 v[14:15], v[188:191], off offset:2048
	ds_read_b128 v[124:127], v57
	s_waitcnt lgkmcnt(7)
	global_store_dwordx4 v[0:1], v[96:99], off offset:2560
	s_waitcnt lgkmcnt(6)
	global_store_dwordx4 v[2:3], v[100:103], off offset:2560
	s_waitcnt lgkmcnt(5)
	global_store_dwordx4 v[4:5], v[104:107], off offset:2560
	s_waitcnt lgkmcnt(4)
	global_store_dwordx4 v[6:7], v[108:111], off offset:2560
	s_waitcnt lgkmcnt(3)
	global_store_dwordx4 v[8:9], v[112:115], off offset:2560
	s_waitcnt lgkmcnt(2)
	global_store_dwordx4 v[10:11], v[116:119], off offset:2560
	s_waitcnt lgkmcnt(1)
	global_store_dwordx4 v[12:13], v[120:123], off offset:2560
	s_waitcnt lgkmcnt(0)
	global_store_dwordx4 v[14:15], v[124:127], off offset:2560
	s_waitcnt vmcnt(16)
	ds_write_b128 v45, v[128:131] offset:9216
	ds_write_b128 v47, v[132:135] offset:9216
	ds_write_b128 v49, v[136:139] offset:9216
	ds_write_b128 v51, v[140:143] offset:9216
	ds_write_b128 v53, v[144:147] offset:9216
	ds_write_b128 v55, v[148:151] offset:9216
	ds_write_b128 v56, v[152:155] offset:9216
	ds_write_b128 v57, v[156:159] offset:9216
	s_mov_b64 s[34:35], 0
